# SwiGLU GEMM epilogues rewritten with packed f32 mul/add (same arithmetic, fewer VALU issues, no serial chains)
# speedup vs baseline: 1.0068x; 1.0068x over previous
; __device__ __forceinline__ unsigned cvt_pk_bf16(float lo, float hi) { unsigned r; asm volatile("v_cvt_pk_bf16_f32 %0, %1, %2" : "=v"(r) : "v"(lo), "v"(hi)); return r; }
; __device__ __forceinline__ float sigmoid_f(float x) { return __builtin_amdgcn_rcpf(1.0f + __expf(-x)); }
;     __device__ __forceinline__ void operator()(const f32x4 (&acc)[2][2][4][2], const Unit& u, int wr, int wc, int fr, int fq) const {
;         const int row0 = u.pm * rowmul + wr * 64 + fr, col0 = (u.pn + pn0) * HALF + wc * 32 + 8 * fq;
; #pragma unroll
;         for (int ai = 0; ai < 2; ++ai) { if (ai * HALF >= rowmul) break;
; #pragma unroll
;             for (int m = 0; m < 4; ++m) { bf16_t* rowp = H + (size_t)(row0 + ai * HALF + m * 16) * ldc + col0;
;                 float hv[8];
; #pragma unroll
;                 for (int n = 0; n < 2; ++n)
; #pragma unroll
;                     for (int i = 0; i < 4; ++i) { const float a = acc[ai][0][m][n][i], b = acc[ai][1][m][n][i]; hv[4 * n + i] = a * sigmoid_f(a) * b; }
;                 u32x4 w; w.x = cvt_pk_bf16(hv[0], hv[1]); w.y = cvt_pk_bf16(hv[2], hv[3]); w.z = cvt_pk_bf16(hv[4], hv[5]); w.w = cvt_pk_bf16(hv[6], hv[7]);
;                 *(u32x4*)rowp = w; } }
.LBB0_398:
	v_lshl_or_b32 v160, s21, 7, v156
	v_lshl_add_u32 v158, s20, 8, v154
	v_ashrrev_i32_e32 v161, 31, v160
	v_mov_b64_e32 v[140:141], s[6:7]
	s_mov_b64 s[20:21], -1
	s_andn2_b64 vcc, exec, s[4:5]
	v_lshlrev_b64 v[160:161], 1, v[160:161]
	v_mov_b32_e32 v204, 0xbfb8aa3b
	v_mad_i64_i32 v[206:207], s[0:1], v158, s33, v[140:141]
	v_lshl_add_u64 v[206:207], v[206:207], 0, v[160:161]
	v_pk_mul_f32 v[200:201], v[126:127], v[204:205] op_sel_hi:[1,0]
	v_pk_mul_f32 v[202:203], v[128:129], v[204:205] op_sel_hi:[1,0]
	v_exp_f32_e32 v200, v200
	v_exp_f32_e32 v201, v201
	v_exp_f32_e32 v202, v202
	v_exp_f32_e32 v203, v203
	v_pk_add_f32 v[200:201], v[200:201], 1.0 op_sel_hi:[1,0]
	v_pk_add_f32 v[202:203], v[202:203], 1.0 op_sel_hi:[1,0]
	v_rcp_f32_e32 v200, v200
	v_rcp_f32_e32 v201, v201
	v_rcp_f32_e32 v202, v202
	v_rcp_f32_e32 v203, v203
	v_pk_mul_f32 v[200:201], v[126:127], v[200:201]
	v_pk_mul_f32 v[202:203], v[128:129], v[202:203]
	v_pk_mul_f32 v[122:123], v[200:201], v[122:123]
	v_pk_mul_f32 v[124:125], v[202:203], v[124:125]
	v_pk_mul_f32 v[200:201], v[118:119], v[204:205] op_sel_hi:[1,0]
	v_pk_mul_f32 v[202:203], v[120:121], v[204:205] op_sel_hi:[1,0]
	v_exp_f32_e32 v200, v200
	v_exp_f32_e32 v201, v201
	v_exp_f32_e32 v202, v202
	v_exp_f32_e32 v203, v203
	v_pk_add_f32 v[200:201], v[200:201], 1.0 op_sel_hi:[1,0]
	v_pk_add_f32 v[202:203], v[202:203], 1.0 op_sel_hi:[1,0]
	v_rcp_f32_e32 v200, v200
	v_rcp_f32_e32 v201, v201
	v_rcp_f32_e32 v202, v202
	v_rcp_f32_e32 v203, v203
	v_pk_mul_f32 v[200:201], v[118:119], v[200:201]
	v_pk_mul_f32 v[202:203], v[120:121], v[202:203]
	v_pk_mul_f32 v[114:115], v[200:201], v[114:115]
	v_pk_mul_f32 v[116:117], v[202:203], v[116:117]
	v_cvt_pk_bf16_f32 v122, v122, v123
	v_cvt_pk_bf16_f32 v123, v124, v125
	v_cvt_pk_bf16_f32 v124, v114, v115
	v_cvt_pk_bf16_f32 v125, v116, v117
	global_store_dwordx4 v[206:207], v[122:125], off
	v_add_u32_e32 v210, 0x10, v158
	v_mad_i64_i32 v[208:209], s[0:1], v210, s33, v[140:141]
	v_lshl_add_u64 v[208:209], v[208:209], 0, v[160:161]
	v_pk_mul_f32 v[200:201], v[110:111], v[204:205] op_sel_hi:[1,0]
	v_pk_mul_f32 v[202:203], v[112:113], v[204:205] op_sel_hi:[1,0]
	v_exp_f32_e32 v200, v200
	v_exp_f32_e32 v201, v201
	v_exp_f32_e32 v202, v202
	v_exp_f32_e32 v203, v203
	v_pk_add_f32 v[200:201], v[200:201], 1.0 op_sel_hi:[1,0]
	v_pk_add_f32 v[202:203], v[202:203], 1.0 op_sel_hi:[1,0]
	v_rcp_f32_e32 v200, v200
	v_rcp_f32_e32 v201, v201
	v_rcp_f32_e32 v202, v202
	v_rcp_f32_e32 v203, v203
	v_pk_mul_f32 v[200:201], v[110:111], v[200:201]
	v_pk_mul_f32 v[202:203], v[112:113], v[202:203]
	v_pk_mul_f32 v[106:107], v[200:201], v[106:107]
	v_pk_mul_f32 v[108:109], v[202:203], v[108:109]
	v_pk_mul_f32 v[200:201], v[102:103], v[204:205] op_sel_hi:[1,0]
	v_pk_mul_f32 v[202:203], v[104:105], v[204:205] op_sel_hi:[1,0]
	v_exp_f32_e32 v200, v200
	v_exp_f32_e32 v201, v201
	v_exp_f32_e32 v202, v202
	v_exp_f32_e32 v203, v203
	v_pk_add_f32 v[200:201], v[200:201], 1.0 op_sel_hi:[1,0]
	v_pk_add_f32 v[202:203], v[202:203], 1.0 op_sel_hi:[1,0]
	v_rcp_f32_e32 v200, v200
	v_rcp_f32_e32 v201, v201
	v_rcp_f32_e32 v202, v202
	v_rcp_f32_e32 v203, v203
	v_pk_mul_f32 v[200:201], v[102:103], v[200:201]
	v_pk_mul_f32 v[202:203], v[104:105], v[202:203]
	v_pk_mul_f32 v[98:99], v[200:201], v[98:99]
	v_pk_mul_f32 v[100:101], v[202:203], v[100:101]
	v_cvt_pk_bf16_f32 v106, v106, v107
	v_cvt_pk_bf16_f32 v107, v108, v109
	v_cvt_pk_bf16_f32 v108, v98, v99
	v_cvt_pk_bf16_f32 v109, v100, v101
	global_store_dwordx4 v[208:209], v[106:109], off
	v_add_u32_e32 v210, 0x20, v158
	v_mad_i64_i32 v[206:207], s[0:1], v210, s33, v[140:141]
	v_lshl_add_u64 v[206:207], v[206:207], 0, v[160:161]
	v_pk_mul_f32 v[200:201], v[94:95], v[204:205] op_sel_hi:[1,0]
	v_pk_mul_f32 v[202:203], v[96:97], v[204:205] op_sel_hi:[1,0]
	v_exp_f32_e32 v200, v200
	v_exp_f32_e32 v201, v201
	v_exp_f32_e32 v202, v202
	v_exp_f32_e32 v203, v203
	v_pk_add_f32 v[200:201], v[200:201], 1.0 op_sel_hi:[1,0]
	v_pk_add_f32 v[202:203], v[202:203], 1.0 op_sel_hi:[1,0]
	v_rcp_f32_e32 v200, v200
	v_rcp_f32_e32 v201, v201
	v_rcp_f32_e32 v202, v202
	v_rcp_f32_e32 v203, v203
	v_pk_mul_f32 v[200:201], v[94:95], v[200:201]
	v_pk_mul_f32 v[202:203], v[96:97], v[202:203]
	v_pk_mul_f32 v[90:91], v[200:201], v[90:91]
	v_pk_mul_f32 v[92:93], v[202:203], v[92:93]
	v_pk_mul_f32 v[200:201], v[86:87], v[204:205] op_sel_hi:[1,0]
	v_pk_mul_f32 v[202:203], v[88:89], v[204:205] op_sel_hi:[1,0]
	v_exp_f32_e32 v200, v200
	v_exp_f32_e32 v201, v201
	v_exp_f32_e32 v202, v202
	v_exp_f32_e32 v203, v203
	v_pk_add_f32 v[200:201], v[200:201], 1.0 op_sel_hi:[1,0]
	v_pk_add_f32 v[202:203], v[202:203], 1.0 op_sel_hi:[1,0]
	v_rcp_f32_e32 v200, v200
	v_rcp_f32_e32 v201, v201
	v_rcp_f32_e32 v202, v202
	v_rcp_f32_e32 v203, v203
	v_pk_mul_f32 v[200:201], v[86:87], v[200:201]
	v_pk_mul_f32 v[202:203], v[88:89], v[202:203]
	v_pk_mul_f32 v[82:83], v[200:201], v[82:83]
	v_pk_mul_f32 v[84:85], v[202:203], v[84:85]
	v_cvt_pk_bf16_f32 v90, v90, v91
	v_cvt_pk_bf16_f32 v91, v92, v93
	v_cvt_pk_bf16_f32 v92, v82, v83
	v_cvt_pk_bf16_f32 v93, v84, v85
	global_store_dwordx4 v[206:207], v[90:93], off
	v_add_u32_e32 v210, 0x30, v158
	v_mad_i64_i32 v[208:209], s[0:1], v210, s33, v[140:141]
	v_lshl_add_u64 v[208:209], v[208:209], 0, v[160:161]
	v_pk_mul_f32 v[200:201], v[78:79], v[204:205] op_sel_hi:[1,0]
	v_pk_mul_f32 v[202:203], v[80:81], v[204:205] op_sel_hi:[1,0]
	v_exp_f32_e32 v200, v200
	v_exp_f32_e32 v201, v201
	v_exp_f32_e32 v202, v202
	v_exp_f32_e32 v203, v203
	v_pk_add_f32 v[200:201], v[200:201], 1.0 op_sel_hi:[1,0]
	v_pk_add_f32 v[202:203], v[202:203], 1.0 op_sel_hi:[1,0]
	v_rcp_f32_e32 v200, v200
	v_rcp_f32_e32 v201, v201
; __device__ __forceinline__ unsigned cvt_pk_bf16(float lo, float hi) { unsigned r; asm volatile("v_cvt_pk_bf16_f32 %0, %1, %2" : "=v"(r) : "v"(lo), "v"(hi)); return r; }
; __device__ __forceinline__ float sigmoid_f(float x) { return __builtin_amdgcn_rcpf(1.0f + __expf(-x)); }
;     __device__ __forceinline__ void operator()(const f32x4 (&acc)[2][2][4][2], const Unit& u, int wr, int wc, int fr, int fq) const {
;         const int row0 = u.pm * rowmul + wr * 64 + fr, col0 = (u.pn + pn0) * HALF + wc * 32 + 8 * fq;
; #pragma unroll
;         for (int ai = 0; ai < 2; ++ai) { if (ai * HALF >= rowmul) break;
; #pragma unroll
;             for (int m = 0; m < 4; ++m) { bf16_t* rowp = H + (size_t)(row0 + ai * HALF + m * 16) * ldc + col0;
;                 float hv[8];
; #pragma unroll
;                 for (int n = 0; n < 2; ++n)
; #pragma unroll
;                     for (int i = 0; i < 4; ++i) { const float a = acc[ai][0][m][n][i], b = acc[ai][1][m][n][i]; hv[4 * n + i] = a * sigmoid_f(a) * b; }
;                 u32x4 w; w.x = cvt_pk_bf16(hv[0], hv[1]); w.y = cvt_pk_bf16(hv[2], hv[3]); w.z = cvt_pk_bf16(hv[4], hv[5]); w.w = cvt_pk_bf16(hv[6], hv[7]);
;                 *(u32x4*)rowp = w; } }
	v_rcp_f32_e32 v202, v202
	v_rcp_f32_e32 v203, v203
	v_pk_mul_f32 v[200:201], v[78:79], v[200:201]
	v_pk_mul_f32 v[202:203], v[80:81], v[202:203]
	v_pk_mul_f32 v[74:75], v[200:201], v[74:75]
	v_pk_mul_f32 v[76:77], v[202:203], v[76:77]
	v_pk_mul_f32 v[200:201], v[70:71], v[204:205] op_sel_hi:[1,0]
	v_pk_mul_f32 v[202:203], v[72:73], v[204:205] op_sel_hi:[1,0]
	v_exp_f32_e32 v200, v200
	v_exp_f32_e32 v201, v201
	v_exp_f32_e32 v202, v202
	v_exp_f32_e32 v203, v203
	v_pk_add_f32 v[200:201], v[200:201], 1.0 op_sel_hi:[1,0]
	v_pk_add_f32 v[202:203], v[202:203], 1.0 op_sel_hi:[1,0]
	v_rcp_f32_e32 v200, v200
	v_rcp_f32_e32 v201, v201
	v_rcp_f32_e32 v202, v202
	v_rcp_f32_e32 v203, v203
	v_pk_mul_f32 v[200:201], v[70:71], v[200:201]
	v_pk_mul_f32 v[202:203], v[72:73], v[202:203]
	v_pk_mul_f32 v[66:67], v[200:201], v[66:67]
	v_pk_mul_f32 v[68:69], v[202:203], v[68:69]
	v_cvt_pk_bf16_f32 v74, v74, v75
	v_cvt_pk_bf16_f32 v75, v76, v77
	v_cvt_pk_bf16_f32 v76, v66, v67
	v_cvt_pk_bf16_f32 v77, v68, v69
	global_store_dwordx4 v[208:209], v[74:77], off
	v_add_u32_e32 v210, 0x80, v158
	v_mad_i64_i32 v[206:207], s[0:1], v210, s33, v[140:141]
	v_lshl_add_u64 v[206:207], v[206:207], 0, v[160:161]
	v_pk_mul_f32 v[200:201], v[62:63], v[204:205] op_sel_hi:[1,0]
	v_pk_mul_f32 v[202:203], v[64:65], v[204:205] op_sel_hi:[1,0]
	v_exp_f32_e32 v200, v200
	v_exp_f32_e32 v201, v201
	v_exp_f32_e32 v202, v202
	v_exp_f32_e32 v203, v203
	v_pk_add_f32 v[200:201], v[200:201], 1.0 op_sel_hi:[1,0]
	v_pk_add_f32 v[202:203], v[202:203], 1.0 op_sel_hi:[1,0]
	v_rcp_f32_e32 v200, v200
	v_rcp_f32_e32 v201, v201
	v_rcp_f32_e32 v202, v202
	v_rcp_f32_e32 v203, v203
	v_pk_mul_f32 v[200:201], v[62:63], v[200:201]
	v_pk_mul_f32 v[202:203], v[64:65], v[202:203]
	v_pk_mul_f32 v[58:59], v[200:201], v[58:59]
	v_pk_mul_f32 v[60:61], v[202:203], v[60:61]
	v_pk_mul_f32 v[200:201], v[54:55], v[204:205] op_sel_hi:[1,0]
	v_pk_mul_f32 v[202:203], v[56:57], v[204:205] op_sel_hi:[1,0]
	v_exp_f32_e32 v200, v200
	v_exp_f32_e32 v201, v201
	v_exp_f32_e32 v202, v202
	v_exp_f32_e32 v203, v203
	v_pk_add_f32 v[200:201], v[200:201], 1.0 op_sel_hi:[1,0]
	v_pk_add_f32 v[202:203], v[202:203], 1.0 op_sel_hi:[1,0]
	v_rcp_f32_e32 v200, v200
	v_rcp_f32_e32 v201, v201
	v_rcp_f32_e32 v202, v202
	v_rcp_f32_e32 v203, v203
	v_pk_mul_f32 v[200:201], v[54:55], v[200:201]
	v_pk_mul_f32 v[202:203], v[56:57], v[202:203]
	v_pk_mul_f32 v[50:51], v[200:201], v[50:51]
	v_pk_mul_f32 v[52:53], v[202:203], v[52:53]
	v_cvt_pk_bf16_f32 v58, v58, v59
	v_cvt_pk_bf16_f32 v59, v60, v61
	v_cvt_pk_bf16_f32 v60, v50, v51
	v_cvt_pk_bf16_f32 v61, v52, v53
	global_store_dwordx4 v[206:207], v[58:61], off
	v_add_u32_e32 v210, 0x90, v158
	v_mad_i64_i32 v[208:209], s[0:1], v210, s33, v[140:141]
	v_lshl_add_u64 v[208:209], v[208:209], 0, v[160:161]
	v_pk_mul_f32 v[200:201], v[46:47], v[204:205] op_sel_hi:[1,0]
	v_pk_mul_f32 v[202:203], v[48:49], v[204:205] op_sel_hi:[1,0]
	v_exp_f32_e32 v200, v200
	v_exp_f32_e32 v201, v201
	v_exp_f32_e32 v202, v202
	v_exp_f32_e32 v203, v203
	v_pk_add_f32 v[200:201], v[200:201], 1.0 op_sel_hi:[1,0]
	v_pk_add_f32 v[202:203], v[202:203], 1.0 op_sel_hi:[1,0]
	v_rcp_f32_e32 v200, v200
	v_rcp_f32_e32 v201, v201
	v_rcp_f32_e32 v202, v202
	v_rcp_f32_e32 v203, v203
	v_pk_mul_f32 v[200:201], v[46:47], v[200:201]
	v_pk_mul_f32 v[202:203], v[48:49], v[202:203]
	v_pk_mul_f32 v[42:43], v[200:201], v[42:43]
	v_pk_mul_f32 v[44:45], v[202:203], v[44:45]
	v_pk_mul_f32 v[200:201], v[38:39], v[204:205] op_sel_hi:[1,0]
	v_pk_mul_f32 v[202:203], v[40:41], v[204:205] op_sel_hi:[1,0]
	v_exp_f32_e32 v200, v200
	v_exp_f32_e32 v201, v201
	v_exp_f32_e32 v202, v202
	v_exp_f32_e32 v203, v203
	v_pk_add_f32 v[200:201], v[200:201], 1.0 op_sel_hi:[1,0]
	v_pk_add_f32 v[202:203], v[202:203], 1.0 op_sel_hi:[1,0]
; __device__ __forceinline__ unsigned cvt_pk_bf16(float lo, float hi) { unsigned r; asm volatile("v_cvt_pk_bf16_f32 %0, %1, %2" : "=v"(r) : "v"(lo), "v"(hi)); return r; }
; __device__ __forceinline__ float sigmoid_f(float x) { return __builtin_amdgcn_rcpf(1.0f + __expf(-x)); }
; #define PG8_BAR __builtin_amdgcn_s_barrier()
;     __device__ __forceinline__ void operator()(const f32x4 (&acc)[2][2][4][2], const Unit& u, int wr, int wc, int fr, int fq) const {
;     ...
;             for (int m = 0; m < 4; ++m) { bf16_t* rowp = H + (size_t)(row0 + ai * HALF + m * 16) * ldc + col0;
;                 float hv[8];
; #pragma unroll
;                 for (int n = 0; n < 2; ++n)
; #pragma unroll
;                     for (int i = 0; i < 4; ++i) { const float a = acc[ai][0][m][n][i], b = acc[ai][1][m][n][i]; hv[4 * n + i] = a * sigmoid_f(a) * b; }
;                 u32x4 w; w.x = cvt_pk_bf16(hv[0], hv[1]); w.y = cvt_pk_bf16(hv[2], hv[3]); w.z = cvt_pk_bf16(hv[4], hv[5]); w.w = cvt_pk_bf16(hv[6], hv[7]);
;                 *(u32x4*)rowp = w; } }
; template <class Epi, class Sched, bool ALIGN_EPI = false, bool SP2 = false, bool HALFM = false>
; __device__ __forceinline__ void gemm_phase(PG8_LAS unsigned char* lds, const Gemm g, const Sched& S, const Epi& E, const int tid_in) {
;     ...
;         cur = nxt; cA = nA; cB = nB; ++ui;
;         if constexpr (ALIGN_EPI) { if (wr == 1) PG8_BAR; }
	v_rcp_f32_e32 v200, v200
	v_rcp_f32_e32 v201, v201
	v_rcp_f32_e32 v202, v202
	v_rcp_f32_e32 v203, v203
	v_pk_mul_f32 v[200:201], v[38:39], v[200:201]
	v_pk_mul_f32 v[202:203], v[40:41], v[202:203]
	v_pk_mul_f32 v[34:35], v[200:201], v[34:35]
	v_pk_mul_f32 v[36:37], v[202:203], v[36:37]
	v_cvt_pk_bf16_f32 v42, v42, v43
	v_cvt_pk_bf16_f32 v43, v44, v45
	v_cvt_pk_bf16_f32 v44, v34, v35
	v_cvt_pk_bf16_f32 v45, v36, v37
	global_store_dwordx4 v[208:209], v[42:45], off
	v_add_u32_e32 v210, 0xa0, v158
	v_mad_i64_i32 v[206:207], s[0:1], v210, s33, v[140:141]
	v_lshl_add_u64 v[206:207], v[206:207], 0, v[160:161]
	v_pk_mul_f32 v[200:201], v[30:31], v[204:205] op_sel_hi:[1,0]
	v_pk_mul_f32 v[202:203], v[32:33], v[204:205] op_sel_hi:[1,0]
	v_exp_f32_e32 v200, v200
	v_exp_f32_e32 v201, v201
	v_exp_f32_e32 v202, v202
	v_exp_f32_e32 v203, v203
	v_pk_add_f32 v[200:201], v[200:201], 1.0 op_sel_hi:[1,0]
	v_pk_add_f32 v[202:203], v[202:203], 1.0 op_sel_hi:[1,0]
	v_rcp_f32_e32 v200, v200
	v_rcp_f32_e32 v201, v201
	v_rcp_f32_e32 v202, v202
	v_rcp_f32_e32 v203, v203
	v_pk_mul_f32 v[200:201], v[30:31], v[200:201]
	v_pk_mul_f32 v[202:203], v[32:33], v[202:203]
	v_pk_mul_f32 v[26:27], v[200:201], v[26:27]
	v_pk_mul_f32 v[28:29], v[202:203], v[28:29]
	v_pk_mul_f32 v[200:201], v[22:23], v[204:205] op_sel_hi:[1,0]
	v_pk_mul_f32 v[202:203], v[24:25], v[204:205] op_sel_hi:[1,0]
	v_exp_f32_e32 v200, v200
	v_exp_f32_e32 v201, v201
	v_exp_f32_e32 v202, v202
	v_exp_f32_e32 v203, v203
	v_pk_add_f32 v[200:201], v[200:201], 1.0 op_sel_hi:[1,0]
	v_pk_add_f32 v[202:203], v[202:203], 1.0 op_sel_hi:[1,0]
	v_rcp_f32_e32 v200, v200
	v_rcp_f32_e32 v201, v201
	v_rcp_f32_e32 v202, v202
	v_rcp_f32_e32 v203, v203
	v_pk_mul_f32 v[200:201], v[22:23], v[200:201]
	v_pk_mul_f32 v[202:203], v[24:25], v[202:203]
	v_pk_mul_f32 v[18:19], v[200:201], v[18:19]
	v_pk_mul_f32 v[20:21], v[202:203], v[20:21]
	v_cvt_pk_bf16_f32 v26, v26, v27
	v_cvt_pk_bf16_f32 v27, v28, v29
	v_cvt_pk_bf16_f32 v28, v18, v19
	v_cvt_pk_bf16_f32 v29, v20, v21
	global_store_dwordx4 v[206:207], v[26:29], off
	v_add_u32_e32 v210, 0xb0, v158
	v_mad_i64_i32 v[208:209], s[0:1], v210, s33, v[140:141]
	v_lshl_add_u64 v[208:209], v[208:209], 0, v[160:161]
	v_pk_mul_f32 v[200:201], v[14:15], v[204:205] op_sel_hi:[1,0]
	v_pk_mul_f32 v[202:203], v[16:17], v[204:205] op_sel_hi:[1,0]
	v_exp_f32_e32 v200, v200
	v_exp_f32_e32 v201, v201
	v_exp_f32_e32 v202, v202
	v_exp_f32_e32 v203, v203
	v_pk_add_f32 v[200:201], v[200:201], 1.0 op_sel_hi:[1,0]
	v_pk_add_f32 v[202:203], v[202:203], 1.0 op_sel_hi:[1,0]
	v_rcp_f32_e32 v200, v200
	v_rcp_f32_e32 v201, v201
	v_rcp_f32_e32 v202, v202
	v_rcp_f32_e32 v203, v203
	v_pk_mul_f32 v[200:201], v[14:15], v[200:201]
	v_pk_mul_f32 v[202:203], v[16:17], v[202:203]
	v_pk_mul_f32 v[10:11], v[200:201], v[10:11]
	v_pk_mul_f32 v[12:13], v[202:203], v[12:13]
	v_pk_mul_f32 v[200:201], v[6:7], v[204:205] op_sel_hi:[1,0]
	v_pk_mul_f32 v[202:203], v[8:9], v[204:205] op_sel_hi:[1,0]
	v_exp_f32_e32 v200, v200
	v_exp_f32_e32 v201, v201
	v_exp_f32_e32 v202, v202
	v_exp_f32_e32 v203, v203
	v_pk_add_f32 v[200:201], v[200:201], 1.0 op_sel_hi:[1,0]
	v_pk_add_f32 v[202:203], v[202:203], 1.0 op_sel_hi:[1,0]
	v_rcp_f32_e32 v200, v200
	v_rcp_f32_e32 v201, v201
	v_rcp_f32_e32 v202, v202
	v_rcp_f32_e32 v203, v203
	v_pk_mul_f32 v[200:201], v[6:7], v[200:201]
	v_pk_mul_f32 v[202:203], v[8:9], v[202:203]
	v_pk_mul_f32 v[2:3], v[200:201], v[2:3]
	v_pk_mul_f32 v[4:5], v[202:203], v[4:5]
	v_cvt_pk_bf16_f32 v10, v10, v11
	v_cvt_pk_bf16_f32 v11, v12, v13
	v_cvt_pk_bf16_f32 v12, v2, v3
	v_cvt_pk_bf16_f32 v13, v4, v5
	global_store_dwordx4 v[208:209], v[10:13], off
	s_cbranch_vccnz .LBB0_391
	s_andn2_b64 vcc, exec, s[8:9]
	s_cbranch_vccnz .LBB0_390
	s_barrier
	s_branch .LBB0_390

; __device__ __forceinline__ unsigned cvt_pk_bf16(float lo, float hi) { unsigned r; asm volatile("v_cvt_pk_bf16_f32 %0, %1, %2" : "=v"(r) : "v"(lo), "v"(hi)); return r; }
; __device__ __forceinline__ float sigmoid_f(float x) { return __builtin_amdgcn_rcpf(1.0f + __expf(-x)); }
;     __device__ __forceinline__ void operator()(const f32x4 (&acc)[2][2][4][2], const Unit& u, int wr, int wc, int fr, int fq) const {
;         const int row0 = u.pm * rowmul + wr * 64 + fr, col0 = (u.pn + pn0) * HALF + wc * 32 + 8 * fq;
; #pragma unroll
;         for (int ai = 0; ai < 2; ++ai) { if (ai * HALF >= rowmul) break;
; #pragma unroll
;             for (int m = 0; m < 4; ++m) { bf16_t* rowp = H + (size_t)(row0 + ai * HALF + m * 16) * ldc + col0;
;                 float hv[8];
; #pragma unroll
;                 for (int n = 0; n < 2; ++n)
; #pragma unroll
;                     for (int i = 0; i < 4; ++i) { const float a = acc[ai][0][m][n][i], b = acc[ai][1][m][n][i]; hv[4 * n + i] = a * sigmoid_f(a) * b; }
;                 u32x4 w; w.x = cvt_pk_bf16(hv[0], hv[1]); w.y = cvt_pk_bf16(hv[2], hv[3]); w.z = cvt_pk_bf16(hv[4], hv[5]); w.w = cvt_pk_bf16(hv[6], hv[7]);
;                 *(u32x4*)rowp = w; } }
.LBB0_422:
	v_lshl_add_u32 v78, s21, 7, v74
	v_lshl_add_u32 v76, s20, 7, v72
	v_ashrrev_i32_e32 v79, 31, v78
	v_mov_b64_e32 v[70:71], s[6:7]
	s_mov_b64 s[20:21], -1
	s_andn2_b64 vcc, exec, s[4:5]
	v_lshlrev_b64 v[78:79], 1, v[78:79]
	v_mov_b32_e32 v104, 0xbfb8aa3b
	v_mad_i64_i32 v[106:107], s[0:1], v76, s33, v[70:71]
	v_lshl_add_u64 v[106:107], v[106:107], 0, v[78:79]
	v_pk_mul_f32 v[100:101], v[62:63], v[104:105] op_sel_hi:[1,0]
	v_pk_mul_f32 v[102:103], v[64:65], v[104:105] op_sel_hi:[1,0]
	v_exp_f32_e32 v100, v100
	v_exp_f32_e32 v101, v101
	v_exp_f32_e32 v102, v102
	v_exp_f32_e32 v103, v103
	v_pk_add_f32 v[100:101], v[100:101], 1.0 op_sel_hi:[1,0]
	v_pk_add_f32 v[102:103], v[102:103], 1.0 op_sel_hi:[1,0]
	v_rcp_f32_e32 v100, v100
	v_rcp_f32_e32 v101, v101
	v_rcp_f32_e32 v102, v102
	v_rcp_f32_e32 v103, v103
	v_pk_mul_f32 v[100:101], v[62:63], v[100:101]
	v_pk_mul_f32 v[102:103], v[64:65], v[102:103]
	v_pk_mul_f32 v[58:59], v[100:101], v[58:59]
	v_pk_mul_f32 v[60:61], v[102:103], v[60:61]
	v_pk_mul_f32 v[100:101], v[54:55], v[104:105] op_sel_hi:[1,0]
	v_pk_mul_f32 v[102:103], v[56:57], v[104:105] op_sel_hi:[1,0]
	v_exp_f32_e32 v100, v100
	v_exp_f32_e32 v101, v101
	v_exp_f32_e32 v102, v102
	v_exp_f32_e32 v103, v103
	v_pk_add_f32 v[100:101], v[100:101], 1.0 op_sel_hi:[1,0]
	v_pk_add_f32 v[102:103], v[102:103], 1.0 op_sel_hi:[1,0]
	v_rcp_f32_e32 v100, v100
	v_rcp_f32_e32 v101, v101
	v_rcp_f32_e32 v102, v102
	v_rcp_f32_e32 v103, v103
	v_pk_mul_f32 v[100:101], v[54:55], v[100:101]
	v_pk_mul_f32 v[102:103], v[56:57], v[102:103]
	v_pk_mul_f32 v[50:51], v[100:101], v[50:51]
	v_pk_mul_f32 v[52:53], v[102:103], v[52:53]
	v_cvt_pk_bf16_f32 v58, v58, v59
	v_cvt_pk_bf16_f32 v59, v60, v61
	v_cvt_pk_bf16_f32 v60, v50, v51
	v_cvt_pk_bf16_f32 v61, v52, v53
	global_store_dwordx4 v[106:107], v[58:61], off
	v_add_u32_e32 v110, 0x10, v76
	v_mad_i64_i32 v[108:109], s[0:1], v110, s33, v[70:71]
	v_lshl_add_u64 v[108:109], v[108:109], 0, v[78:79]
	v_pk_mul_f32 v[100:101], v[46:47], v[104:105] op_sel_hi:[1,0]
	v_pk_mul_f32 v[102:103], v[48:49], v[104:105] op_sel_hi:[1,0]
	v_exp_f32_e32 v100, v100
	v_exp_f32_e32 v101, v101
	v_exp_f32_e32 v102, v102
	v_exp_f32_e32 v103, v103
	v_pk_add_f32 v[100:101], v[100:101], 1.0 op_sel_hi:[1,0]
	v_pk_add_f32 v[102:103], v[102:103], 1.0 op_sel_hi:[1,0]
	v_rcp_f32_e32 v100, v100
	v_rcp_f32_e32 v101, v101
	v_rcp_f32_e32 v102, v102
	v_rcp_f32_e32 v103, v103
	v_pk_mul_f32 v[100:101], v[46:47], v[100:101]
	v_pk_mul_f32 v[102:103], v[48:49], v[102:103]
	v_pk_mul_f32 v[42:43], v[100:101], v[42:43]
	v_pk_mul_f32 v[44:45], v[102:103], v[44:45]
	v_pk_mul_f32 v[100:101], v[38:39], v[104:105] op_sel_hi:[1,0]
	v_pk_mul_f32 v[102:103], v[40:41], v[104:105] op_sel_hi:[1,0]
	v_exp_f32_e32 v100, v100
	v_exp_f32_e32 v101, v101
	v_exp_f32_e32 v102, v102
	v_exp_f32_e32 v103, v103
	v_pk_add_f32 v[100:101], v[100:101], 1.0 op_sel_hi:[1,0]
	v_pk_add_f32 v[102:103], v[102:103], 1.0 op_sel_hi:[1,0]
	v_rcp_f32_e32 v100, v100
	v_rcp_f32_e32 v101, v101
	v_rcp_f32_e32 v102, v102
	v_rcp_f32_e32 v103, v103
	v_pk_mul_f32 v[100:101], v[38:39], v[100:101]
	v_pk_mul_f32 v[102:103], v[40:41], v[102:103]
	v_pk_mul_f32 v[34:35], v[100:101], v[34:35]
	v_pk_mul_f32 v[36:37], v[102:103], v[36:37]
	v_cvt_pk_bf16_f32 v42, v42, v43
	v_cvt_pk_bf16_f32 v43, v44, v45
	v_cvt_pk_bf16_f32 v44, v34, v35
	v_cvt_pk_bf16_f32 v45, v36, v37
	global_store_dwordx4 v[108:109], v[42:45], off
	v_add_u32_e32 v110, 0x20, v76
	v_mad_i64_i32 v[106:107], s[0:1], v110, s33, v[70:71]
	v_lshl_add_u64 v[106:107], v[106:107], 0, v[78:79]
	v_pk_mul_f32 v[100:101], v[30:31], v[104:105] op_sel_hi:[1,0]
	v_pk_mul_f32 v[102:103], v[32:33], v[104:105] op_sel_hi:[1,0]
	v_exp_f32_e32 v100, v100
	v_exp_f32_e32 v101, v101
	v_exp_f32_e32 v102, v102
	v_exp_f32_e32 v103, v103
	v_pk_add_f32 v[100:101], v[100:101], 1.0 op_sel_hi:[1,0]
	v_pk_add_f32 v[102:103], v[102:103], 1.0 op_sel_hi:[1,0]
	v_rcp_f32_e32 v100, v100
	v_rcp_f32_e32 v101, v101
	v_rcp_f32_e32 v102, v102
	v_rcp_f32_e32 v103, v103
	v_pk_mul_f32 v[100:101], v[30:31], v[100:101]
	v_pk_mul_f32 v[102:103], v[32:33], v[102:103]
	v_pk_mul_f32 v[26:27], v[100:101], v[26:27]
	v_pk_mul_f32 v[28:29], v[102:103], v[28:29]
	v_pk_mul_f32 v[100:101], v[22:23], v[104:105] op_sel_hi:[1,0]
	v_pk_mul_f32 v[102:103], v[24:25], v[104:105] op_sel_hi:[1,0]
	v_exp_f32_e32 v100, v100
	v_exp_f32_e32 v101, v101
	v_exp_f32_e32 v102, v102
	v_exp_f32_e32 v103, v103
	v_pk_add_f32 v[100:101], v[100:101], 1.0 op_sel_hi:[1,0]
	v_pk_add_f32 v[102:103], v[102:103], 1.0 op_sel_hi:[1,0]
	v_rcp_f32_e32 v100, v100
	v_rcp_f32_e32 v101, v101
	v_rcp_f32_e32 v102, v102
	v_rcp_f32_e32 v103, v103
	v_pk_mul_f32 v[100:101], v[22:23], v[100:101]
	v_pk_mul_f32 v[102:103], v[24:25], v[102:103]
	v_pk_mul_f32 v[18:19], v[100:101], v[18:19]
	v_pk_mul_f32 v[20:21], v[102:103], v[20:21]
	v_cvt_pk_bf16_f32 v26, v26, v27
	v_cvt_pk_bf16_f32 v27, v28, v29
	v_cvt_pk_bf16_f32 v28, v18, v19
	v_cvt_pk_bf16_f32 v29, v20, v21
	global_store_dwordx4 v[106:107], v[26:29], off
	v_add_u32_e32 v110, 0x30, v76
	v_mad_i64_i32 v[108:109], s[0:1], v110, s33, v[70:71]
	v_lshl_add_u64 v[108:109], v[108:109], 0, v[78:79]
	v_pk_mul_f32 v[100:101], v[14:15], v[104:105] op_sel_hi:[1,0]
	v_pk_mul_f32 v[102:103], v[16:17], v[104:105] op_sel_hi:[1,0]
	v_exp_f32_e32 v100, v100
	v_exp_f32_e32 v101, v101
	v_exp_f32_e32 v102, v102
	v_exp_f32_e32 v103, v103
	v_pk_add_f32 v[100:101], v[100:101], 1.0 op_sel_hi:[1,0]
	v_pk_add_f32 v[102:103], v[102:103], 1.0 op_sel_hi:[1,0]
	v_rcp_f32_e32 v100, v100
	v_rcp_f32_e32 v101, v101
	v_rcp_f32_e32 v102, v102
	v_rcp_f32_e32 v103, v103
	v_pk_mul_f32 v[100:101], v[14:15], v[100:101]
	v_pk_mul_f32 v[102:103], v[16:17], v[102:103]
	v_pk_mul_f32 v[10:11], v[100:101], v[10:11]
	v_pk_mul_f32 v[12:13], v[102:103], v[12:13]
	v_pk_mul_f32 v[100:101], v[6:7], v[104:105] op_sel_hi:[1,0]
	v_pk_mul_f32 v[102:103], v[8:9], v[104:105] op_sel_hi:[1,0]
	v_exp_f32_e32 v100, v100
	v_exp_f32_e32 v101, v101
	v_exp_f32_e32 v102, v102
	v_exp_f32_e32 v103, v103
	v_pk_add_f32 v[100:101], v[100:101], 1.0 op_sel_hi:[1,0]
	v_pk_add_f32 v[102:103], v[102:103], 1.0 op_sel_hi:[1,0]
	v_rcp_f32_e32 v100, v100
	v_rcp_f32_e32 v101, v101
	v_rcp_f32_e32 v102, v102
	v_rcp_f32_e32 v103, v103
	v_pk_mul_f32 v[100:101], v[6:7], v[100:101]
	v_pk_mul_f32 v[102:103], v[8:9], v[102:103]
	v_pk_mul_f32 v[2:3], v[100:101], v[2:3]
	v_pk_mul_f32 v[4:5], v[102:103], v[4:5]
	v_cvt_pk_bf16_f32 v10, v10, v11
	v_cvt_pk_bf16_f32 v11, v12, v13
	v_cvt_pk_bf16_f32 v12, v2, v3
	v_cvt_pk_bf16_f32 v13, v4, v5
	global_store_dwordx4 v[108:109], v[10:13], off
	s_cbranch_vccnz .LBB0_411
	s_andn2_b64 vcc, exec, s[8:9]
	s_cbranch_vccnz .LBB0_410
	s_barrier
	s_branch .LBB0_410
